# seams: early L2 write-back started by the fifth-to-last arriver on the XCD (vAdd 4)
# baseline (speedup 1.0000x reference)
; __device__ __forceinline__ unsigned xb_ld(unsigned* p)              { return __hip_atomic_load(p, __ATOMIC_RELAXED, __HIP_MEMORY_SCOPE_AGENT); }
; __device__ __forceinline__ unsigned xb_add(unsigned* p, unsigned v) { return __hip_atomic_fetch_add(p, v, __ATOMIC_RELAXED, __HIP_MEMORY_SCOPE_AGENT); }
; #define XB_SPIN(cond, bar) do { unsigned _sp = 0; while (cond) { __builtin_amdgcn_s_sleep(1); \
;     if ((++_sp & 255u) == 0u) { if (xb_ld(&(bar)[XB_TMO])) break; if (_sp > XB_SPIN_CAP) { atomicAdd(&(bar)[XB_TMO], 1u); break; } } } } while (0)
; __device__ __forceinline__ void xcd_barrier(const XcdBarrier& b, const int wv) {
;     ...
;         unsigned nloc = b.st[0], nx = b.st[1];
;         if (nloc == 0u) { xcd_barrier_complete(bar, b.x, nloc, nx); b.st[0] = nloc; b.st[1] = nx; }
;         const unsigned old = xb_add(&bar[XB_XSUB(b.x)], 1u);
;         const unsigned gen = old / nloc;
;         if (old + 1u == (gen + 1u) * nloc) {
;             __builtin_amdgcn_fence(__ATOMIC_RELEASE, "agent");
;             asm volatile("s_waitcnt vmcnt(0)" ::: "memory");
;             const unsigned og = xb_add(&bar[XB_TOP], 1u);
;             const unsigned tg = og / nx;
;             if (og + 1u == (tg + 1u) * nx) xb_add(&bar[XB_TOPGEN], 1u);
;             else XB_SPIN(xb_ld(&bar[XB_TOPGEN]) == tg, bar);
.Lseam1_328:
	s_or_b64 exec, exec, s[14:15]
	v_cvt_f32_u32_e32 v4, v2
	s_waitcnt vmcnt(0)
	v_readfirstlane_b32 s3, v3
	v_sub_u32_e32 v3, 0, v2
	v_rcp_iflag_f32_e32 v4, v4
	v_add_u32_e32 v5, s3, v1
	v_mul_f32_e32 v4, 0x4f7ffffe, v4
	v_cvt_u32_f32_e32 v4, v4
	v_mul_lo_u32 v1, v3, v4
	v_mul_hi_u32 v1, v4, v1
	v_add_u32_e32 v1, v4, v1
	v_mul_hi_u32 v1, v5, v1
	v_mul_lo_u32 v3, v1, v2
	v_sub_u32_e32 v3, v5, v3
	v_add_u32_e32 v4, 1, v1
	v_cmp_ge_u32_e32 vcc, v3, v2
	s_nop 1
	v_cndmask_b32_e32 v1, v1, v4, vcc
	v_sub_u32_e32 v4, v3, v2
	v_cndmask_b32_e32 v3, v3, v4, vcc
	v_add_u32_e32 v4, 1, v1
	v_cmp_ge_u32_e32 vcc, v3, v2
	v_add_u32_e32 v3, 1, v5
	s_nop 0
	v_cndmask_b32_e32 v1, v1, v4, vcc
	v_mul_lo_u32 v4, v2, v1
	v_add_u32_e32 v2, v4, v2
	v_cmp_ne_u32_e32 vcc, v3, v2
	s_and_saveexec_b64 s[12:13], vcc
	s_xor_b64 s[12:13], exec, s[12:13]
	s_cbranch_execz .Lseam1_342
	v_add_u32_e32 v19, 4, v3
	v_cmp_eq_u32_e32 vcc, v19, v2
	s_cbranch_vccz .Lpf2_0
	buffer_wbl2 sc1

; __device__ __forceinline__ unsigned xb_ld(unsigned* p)              { return __hip_atomic_load(p, __ATOMIC_RELAXED, __HIP_MEMORY_SCOPE_AGENT); }
; __device__ __forceinline__ unsigned xb_add(unsigned* p, unsigned v) { return __hip_atomic_fetch_add(p, v, __ATOMIC_RELAXED, __HIP_MEMORY_SCOPE_AGENT); }
; #define XB_SPIN(cond, bar) do { unsigned _sp = 0; while (cond) { __builtin_amdgcn_s_sleep(1); \
;     if ((++_sp & 255u) == 0u) { if (xb_ld(&(bar)[XB_TMO])) break; if (_sp > XB_SPIN_CAP) { atomicAdd(&(bar)[XB_TMO], 1u); break; } } } } while (0)
; __device__ __forceinline__ void xcd_barrier(const XcdBarrier& b, const int wv) {
;     ...
;         unsigned nloc = b.st[0], nx = b.st[1];
;         if (nloc == 0u) { xcd_barrier_complete(bar, b.x, nloc, nx); b.st[0] = nloc; b.st[1] = nx; }
;         const unsigned old = xb_add(&bar[XB_XSUB(b.x)], 1u);
;         const unsigned gen = old / nloc;
;         if (old + 1u == (gen + 1u) * nloc) {
;             __builtin_amdgcn_fence(__ATOMIC_RELEASE, "agent");
;             asm volatile("s_waitcnt vmcnt(0)" ::: "memory");
;             const unsigned og = xb_add(&bar[XB_TOP], 1u);
;             const unsigned tg = og / nx;
;             if (og + 1u == (tg + 1u) * nx) xb_add(&bar[XB_TOPGEN], 1u);
;             else XB_SPIN(xb_ld(&bar[XB_TOPGEN]) == tg, bar);
.LBB0_727:
	s_or_b64 exec, exec, s[16:17]
	v_cvt_f32_u32_e32 v4, v2
	s_waitcnt vmcnt(0)
	v_readfirstlane_b32 s3, v3
	v_sub_u32_e32 v3, 0, v2
	v_rcp_iflag_f32_e32 v4, v4
	v_add_u32_e32 v5, s3, v1
	v_mul_f32_e32 v4, 0x4f7ffffe, v4
	v_cvt_u32_f32_e32 v4, v4
	v_mul_lo_u32 v1, v3, v4
	v_mul_hi_u32 v1, v4, v1
	v_add_u32_e32 v1, v4, v1
	v_mul_hi_u32 v1, v5, v1
	v_mul_lo_u32 v3, v1, v2
	v_sub_u32_e32 v3, v5, v3
	v_add_u32_e32 v4, 1, v1
	v_cmp_ge_u32_e32 vcc, v3, v2
	s_nop 1
	v_cndmask_b32_e32 v1, v1, v4, vcc
	v_sub_u32_e32 v4, v3, v2
	v_cndmask_b32_e32 v3, v3, v4, vcc
	v_add_u32_e32 v4, 1, v1
	v_cmp_ge_u32_e32 vcc, v3, v2
	v_add_u32_e32 v3, 1, v5
	s_nop 0
	v_cndmask_b32_e32 v1, v1, v4, vcc
	v_mul_lo_u32 v4, v2, v1
	v_add_u32_e32 v2, v4, v2
	v_cmp_ne_u32_e32 vcc, v3, v2
	s_and_saveexec_b64 s[14:15], vcc
	s_xor_b64 s[14:15], exec, s[14:15]
	s_cbranch_execz .LBB0_741
	v_add_u32_e32 v19, 4, v3
	v_cmp_eq_u32_e32 vcc, v19, v2
	s_cbranch_vccz .Lpf2_4
	buffer_wbl2 sc1

; __device__ __forceinline__ unsigned xb_ld(unsigned* p)              { return __hip_atomic_load(p, __ATOMIC_RELAXED, __HIP_MEMORY_SCOPE_AGENT); }
; __device__ __forceinline__ unsigned xb_add(unsigned* p, unsigned v) { return __hip_atomic_fetch_add(p, v, __ATOMIC_RELAXED, __HIP_MEMORY_SCOPE_AGENT); }
; #define XB_SPIN(cond, bar) do { unsigned _sp = 0; while (cond) { __builtin_amdgcn_s_sleep(1); \
;     if ((++_sp & 255u) == 0u) { if (xb_ld(&(bar)[XB_TMO])) break; if (_sp > XB_SPIN_CAP) { atomicAdd(&(bar)[XB_TMO], 1u); break; } } } } while (0)
; __device__ __forceinline__ void xcd_barrier(const XcdBarrier& b, const int wv) {
;     ...
;         unsigned nloc = b.st[0], nx = b.st[1];
;         if (nloc == 0u) { xcd_barrier_complete(bar, b.x, nloc, nx); b.st[0] = nloc; b.st[1] = nx; }
;         const unsigned old = xb_add(&bar[XB_XSUB(b.x)], 1u);
;         const unsigned gen = old / nloc;
;         if (old + 1u == (gen + 1u) * nloc) {
;             __builtin_amdgcn_fence(__ATOMIC_RELEASE, "agent");
;             asm volatile("s_waitcnt vmcnt(0)" ::: "memory");
;             const unsigned og = xb_add(&bar[XB_TOP], 1u);
;             const unsigned tg = og / nx;
;             if (og + 1u == (tg + 1u) * nx) xb_add(&bar[XB_TOPGEN], 1u);
;             else XB_SPIN(xb_ld(&bar[XB_TOPGEN]) == tg, bar);
.LBB0_860:
	s_or_b64 exec, exec, s[18:19]
	v_cvt_f32_u32_e32 v4, v2
	s_waitcnt vmcnt(0)
	v_readfirstlane_b32 s3, v3
	v_sub_u32_e32 v3, 0, v2
	v_rcp_iflag_f32_e32 v4, v4
	v_add_u32_e32 v5, s3, v1
	v_mul_f32_e32 v4, 0x4f7ffffe, v4
	v_cvt_u32_f32_e32 v4, v4
	v_mul_lo_u32 v1, v3, v4
	v_mul_hi_u32 v1, v4, v1
	v_add_u32_e32 v1, v4, v1
	v_mul_hi_u32 v1, v5, v1
	v_mul_lo_u32 v3, v1, v2
	v_sub_u32_e32 v3, v5, v3
	v_add_u32_e32 v4, 1, v1
	v_cmp_ge_u32_e32 vcc, v3, v2
	s_nop 1
	v_cndmask_b32_e32 v1, v1, v4, vcc
	v_sub_u32_e32 v4, v3, v2
	v_cndmask_b32_e32 v3, v3, v4, vcc
	v_add_u32_e32 v4, 1, v1
	v_cmp_ge_u32_e32 vcc, v3, v2
	v_add_u32_e32 v3, 1, v5
	s_nop 0
	v_cndmask_b32_e32 v1, v1, v4, vcc
	v_mul_lo_u32 v4, v2, v1
	v_add_u32_e32 v2, v4, v2
	v_cmp_ne_u32_e32 vcc, v3, v2
	s_and_saveexec_b64 s[16:17], vcc
	s_xor_b64 s[16:17], exec, s[16:17]
	s_cbranch_execz .LBB0_874
	v_add_u32_e32 v19, 4, v3
	v_cmp_eq_u32_e32 vcc, v19, v2
	s_cbranch_vccz .Lpf2_6
	buffer_wbl2 sc1
